# attention loop latch/head pinned to a 64-byte boundary (pad in unreachable spot)
# speedup vs baseline: 1.0408x; 1.0408x over previous
; __device__ void item_attn(PP p, int qb, int b, int hh, u16* lds) {
;     ...
;   AStage A, B;
;   as_load(B, kg, vg, 0);
;   as_load(A, kg, vg, 1);
;   as_store(B, lds, kl0, kl1, kl2, vl);
;   __syncthreads();
;   for (int kt = 0; kt < ntiles; kt += 2) {
.LBB0_453:
	s_and_b64 vcc, exec, s[40:41]
	s_waitcnt lgkmcnt(0)
	s_barrier
	s_cbranch_vccnz .LBB0_477
	v_mov_b32_e32 v90, v214
	v_mov_b32_e32 v91, v215
	v_mov_b32_e32 v92, v216
	v_mov_b32_e32 v93, v217
	v_mov_b32_e32 v94, v218
	v_mov_b32_e32 v95, v219
	v_mov_b32_e32 v96, v220
	v_mov_b32_e32 v97, v221
	v_mov_b32_e32 v106, v222
	s_mov_b32 s45, 3
	s_branch .LBB0_456
	.p2align	6
